# two-phase dilated attention, phase B walks heads in reverse order (reads what phase A wrote last first)
# baseline (speedup 1.0000x reference)
; #define LAS __attribute__((address_space(3)))
; __device__ __forceinline__ void issue(const u16* __restrict__ QKV, int task, int tid, v4u (&pk)[6], v4u (&pv)[6], bf16x8 (&qn)[4]) {
;     const Dec d = decode(task); const int lane = tid & 63, w = tid >> 6, r = lane & 31, h = lane >> 5;
; #pragma unroll
;     for (int n = 0; n < 6; ++n) { const int id = tid + 512 * n, c = id >> 3, ch = id & 7; int ki = d.i0 - 128 + c; ki = ki < 0 ? 0 : ki;
;     ...
;         pk[n] = *(const v4u*)(src + 1024); pv[n] = *(const v4u*)(src + 2048); }
;     ...
; #pragma unroll
;     for (int ks = 0; ks < 4; ++ks) qn[ks] = *(const bf16x8*)(qp + 16 * ks + 8 * h);
; }
; __device__ __forceinline__ void phase(LAS unsigned char* L, const u16* __restrict__ QKV, u16* OBg0, u16* OBg1, u16* OBg2, float* LSE, int first, int stride, const int tid) {
;     const int lane = tid & 63, w = __builtin_amdgcn_readfirstlane(tid >> 6), r = lane & 31, h = lane >> 5;
;     const bool xl = (stride == 256); const int nround = xl ? 24 : (6144 - first + stride - 1) / stride;
;     if (first >= 6144) return;
;     ...
;     v4u pk[6], pv[6]; bf16x8 qn[4];
;     issue(QKV, DL_TASK(0), tid, pk, pv, qn);
.Ldb_468:
	v_readlane_b32 s2, v255, 26
	v_readlane_b32 s3, v255, 27
	s_andn2_b64 vcc, exec, s[2:3]
	s_cbranch_vccnz .LBB0_510
	s_cmp_lt_i32 s6, 1
	s_cbranch_scc1 .LBB0_510
	v_ashrrev_i32_e32 v4, 1, v3
	v_and_b32_e32 v5, 0xffffffe0, v4
	s_movk_i32 s11, 0xffe0
	v_readlane_b32 s1, v255, 36
	s_lshr_b32 s98, s1, 8
	s_and_b32 s1, s98, 1
	s_lshl_b32 s1, s1, 8
	s_add_i32 s99, s1, 0xffffff80
	s_lshr_b32 s98, s98, 1
	v_and_b32_e32 v162, 31, v3
	v_bfi_b32 v169, s11, v4, v3
	v_add_u32_e32 v4, s1, v5
	v_add_u32_e32 v0, 0x200, v3
	v_or_b32_e32 v4, v4, v162
	s_mov_b32 s1, 4
	v_ashrrev_i32_e32 v164, 3, v0
	v_add_u32_e32 v0, 0x400, v3
	v_lshlrev_b32_e32 v4, s1, v4
	v_readlane_b32 s4, v255, 31
	v_readlane_b32 s8, v255, 34
	v_ashrrev_i32_e32 v165, 3, v0
	v_add_u32_e32 v0, 0x600, v3
	v_ashrrev_i32_e32 v5, 31, v4
	v_readlane_b32 s5, v255, 32
	s_or_b32 s4, s4, s98
	v_readlane_b32 s9, v255, 35
	s_add_u32 s8, s8, 0x380
	s_addc_u32 s9, s9, 0
	v_ashrrev_i32_e32 v166, 3, v0
	v_add_u32_e32 v0, 0x800, v3
	v_lshl_add_u64 v[4:5], s[4:5], 0, v[4:5]
	v_mov_b64_e32 v[6:7], s[8:9]
	s_movk_i32 s10, 0x1800
	v_ashrrev_i32_e32 v167, 3, v0
	v_add_u32_e32 v0, 0xa00, v3
	v_mad_u64_u32 v[6:7], s[2:3], v4, s10, v[6:7]
	v_ashrrev_i32_e32 v168, 3, v0
	v_lshrrev_b32_e32 v0, 2, v3
	v_mov_b32_e32 v4, v7
	v_and_b32_e32 v2, 8, v0
	v_mad_u64_u32 v[4:5], s[2:3], v5, s10, v[4:5]
	v_lshlrev_b32_e32 v0, 4, v3
	v_mov_b32_e32 v7, v4
	v_lshlrev_b32_e32 v4, 1, v2
	v_mov_b32_e32 v5, v1
	v_and_b32_e32 v0, 0x70, v0
	v_lshl_add_u64 v[4:5], v[6:7], 0, v[4:5]
	global_load_dwordx4 v[146:149], v[4:5], off offset:96
	global_load_dwordx4 v[150:153], v[4:5], off offset:64
	global_load_dwordx4 v[154:157], v[4:5], off offset:32
	global_load_dwordx4 v[66:69], v[4:5], off
	v_lshl_add_u64 v[4:5], s[8:9], 0, v[0:1]
	s_mov_b32 s8, s99
	s_movk_i32 s9, 0x1000
	v_ashrrev_i32_e32 v163, 3, v3
	v_add_u32_e32 v6, s8, v168
	v_max_i32_e32 v6, 0, v6
	v_lshlrev_b32_e32 v6, s1, v6
	v_ashrrev_i32_e32 v7, 31, v6
	v_lshl_add_u64 v[6:7], s[4:5], 0, v[6:7]
	v_mad_u64_u32 v[8:9], s[2:3], v6, s10, v[4:5]
	v_mov_b32_e32 v6, v9
	v_mad_u64_u32 v[6:7], s[2:3], v7, s10, v[6:7]
	v_add_co_u32_e32 v10, vcc, s9, v8
	v_mov_b32_e32 v9, v6
	s_nop 0
	v_addc_co_u32_e32 v11, vcc, 0, v6, vcc
	v_add_u32_e32 v6, s8, v167
	v_max_i32_e32 v6, 0, v6
	v_lshlrev_b32_e32 v6, s1, v6
	v_ashrrev_i32_e32 v7, 31, v6
	v_lshl_add_u64 v[6:7], s[4:5], 0, v[6:7]
	v_mad_u64_u32 v[12:13], s[2:3], v6, s10, v[4:5]
	v_mov_b32_e32 v6, v13
	v_mad_u64_u32 v[6:7], s[2:3], v7, s10, v[6:7]
	v_add_co_u32_e32 v14, vcc, s9, v12
	v_mov_b32_e32 v13, v6
	s_nop 0
	v_addc_co_u32_e32 v15, vcc, 0, v6, vcc
	v_add_u32_e32 v6, s8, v166
	v_max_i32_e32 v6, 0, v6
	v_lshlrev_b32_e32 v6, s1, v6
	v_ashrrev_i32_e32 v7, 31, v6
	v_lshl_add_u64 v[6:7], s[4:5], 0, v[6:7]
	global_load_dwordx4 v[94:97], v[10:11], off
	global_load_dwordx4 v[90:93], v[14:15], off
	global_load_dwordx4 v[86:89], v[8:9], off offset:2048
	global_load_dwordx4 v[82:85], v[12:13], off offset:2048
	v_mad_u64_u32 v[8:9], s[2:3], v6, s10, v[4:5]
	v_mov_b32_e32 v6, v9
	v_mad_u64_u32 v[6:7], s[2:3], v7, s10, v[6:7]
	v_add_co_u32_e32 v10, vcc, s9, v8
	v_mov_b32_e32 v9, v6
	s_nop 0
	v_addc_co_u32_e32 v11, vcc, 0, v6, vcc
	v_add_u32_e32 v6, s8, v165
	v_max_i32_e32 v6, 0, v6
	v_lshlrev_b32_e32 v6, s1, v6
	v_ashrrev_i32_e32 v7, 31, v6
	v_lshl_add_u64 v[6:7], s[4:5], 0, v[6:7]
	v_mad_u64_u32 v[12:13], s[2:3], v6, s10, v[4:5]
	v_mov_b32_e32 v6, v13
	v_mad_u64_u32 v[6:7], s[2:3], v7, s10, v[6:7]
	v_add_co_u32_e32 v14, vcc, s9, v12
	v_mov_b32_e32 v13, v6
	s_nop 0
	v_addc_co_u32_e32 v15, vcc, 0, v6, vcc
	v_add_u32_e32 v6, s8, v164
	v_max_i32_e32 v6, 0, v6
	v_lshlrev_b32_e32 v6, s1, v6
	v_ashrrev_i32_e32 v7, 31, v6
	v_lshl_add_u64 v[6:7], s[4:5], 0, v[6:7]
	global_load_dwordx4 v[110:113], v[10:11], off
	global_load_dwordx4 v[106:109], v[14:15], off
	global_load_dwordx4 v[102:105], v[8:9], off offset:2048
	global_load_dwordx4 v[98:101], v[12:13], off offset:2048
	v_mad_u64_u32 v[8:9], s[2:3], v6, s10, v[4:5]
	v_mov_b32_e32 v6, v9
	v_mad_u64_u32 v[6:7], s[2:3], v7, s10, v[6:7]
	v_add_co_u32_e32 v10, vcc, s9, v8
	v_mov_b32_e32 v9, v6
	s_nop 0
	v_addc_co_u32_e32 v11, vcc, 0, v6, vcc
	v_add_u32_e32 v6, s8, v163
	v_max_i32_e32 v6, 0, v6
	v_lshlrev_b32_e32 v6, s1, v6
	v_ashrrev_i32_e32 v7, 31, v6
	v_lshl_add_u64 v[6:7], s[4:5], 0, v[6:7]
	v_mad_u64_u32 v[4:5], s[2:3], v6, s10, v[4:5]
	v_mov_b32_e32 v6, v5
; __device__ __forceinline__ void issue(const u16* __restrict__ QKV, int task, int tid, v4u (&pk)[6], v4u (&pv)[6], bf16x8 (&qn)[4]) {
;     ...
;     for (int n = 0; n < 6; ++n) { const int id = tid + 512 * n, c = id >> 3, ch = id & 7; int ki = d.i0 - 128 + c; ki = ki < 0 ? 0 : ki;
;     ...
;         pk[n] = *(const v4u*)(src + 1024); pv[n] = *(const v4u*)(src + 2048); }
;     ...
; #pragma unroll
;     for (int ks = 0; ks < 4; ++ks) qn[ks] = *(const bf16x8*)(qp + 16 * ks + 8 * h);
; }
; __device__ __forceinline__ void phase(LAS unsigned char* L, const u16* __restrict__ QKV, u16* OBg0, u16* OBg1, u16* OBg2, float* LSE, int first, int stride, const int tid) {
;     const int lane = tid & 63, w = __builtin_amdgcn_readfirstlane(tid >> 6), r = lane & 31, h = lane >> 5;
;     const bool xl = (stride == 256); const int nround = xl ? 24 : (6144 - first + stride - 1) / stride;
;     if (first >= 6144) return;
;     ...
;     v4u pk[6], pv[6]; bf16x8 qn[4];
;     issue(QKV, DL_TASK(0), tid, pk, pv, qn);
;     for (int kr = 0; kr < nround; ++kr) {
;         const int task = DL_TASK(kr);
;         const Dec d = decode(task);
; #pragma unroll
;         for (int n = 0; n < 6; ++n) { const int id = tid + 512 * n, c = id >> 3, ch = id & 7; *(LAS v4u*)(L + O_K + c * KP + ch * 16) = pk[n]; *(LAS v4u*)(L + O_V + c * VP + ch * 16) = pv[n]; }
;         bf16x8 qf[4];
; #pragma unroll
;         for (int ks = 0; ks < 4; ++ks) qf[ks] = qn[ks];
;         __syncthreads();
;         if (kr + 1 < nround) issue(QKV, DL_TASK(kr + 1), tid, pk, pv, qn);
;     ...
;         const int qpos = d.res + ((i0 + 32 * w + r) << sh);
;         f32x16 X[5];
; #pragma unroll
;         for (int kb = 0; kb < 5; ++kb) X[kb] = f32x16{};
;         {
;             LAS unsigned char* kbase = L + O_K + (32 * w + r) * KP + 8 * h * 2;
; #pragma unroll
;             for (int ks = 0; ks < 4; ++ks) {
;                 bf16x8 kf[5];
; #pragma unroll
;                 for (int kb = 0; kb < 5; ++kb) kf[kb] = *(LAS bf16x8*)(kbase + 32 * kb * KP + 16 * ks * 2);
; #pragma unroll
;                 for (int kb = 0; kb < 5; ++kb) X[kb] = MFMA32(kf[kb], qf[ks], X[kb]);
;             }
;         }
;         float m = -INFINITY;
;         const int kneg = 128 - i0 - 32 * w;
; #pragma unroll
;         for (int i = 0; i < 16; ++i) { const int c = crow(i, h);
;             X[0][i] = (c >= r && c >= kneg) ? X[0][i] : -INFINITY; X[4][i] = (c <= r) ? X[4][i] : -INFINITY; }
	v_mad_u64_u32 v[6:7], s[2:3], v7, s10, v[6:7]
	v_add_co_u32_e32 v12, vcc, s9, v4
	v_mov_b32_e32 v5, v6
	s_nop 0
	v_addc_co_u32_e32 v13, vcc, 0, v6, vcc
	global_load_dwordx4 v[126:129], v[10:11], off
	global_load_dwordx4 v[122:125], v[12:13], off
	global_load_dwordx4 v[118:121], v[8:9], off offset:2048
	global_load_dwordx4 v[114:117], v[4:5], off offset:2048
	v_bfe_u32 v17, v3, 5, 1
	v_writelane_b32 v254, s58, 14
	v_lshlrev_b32_e32 v170, 2, v17
	v_cmp_gt_u32_e64 s[4:5], v170, v162
	v_writelane_b32 v254, s59, 15
	v_or_b32_e32 v185, 26, v170
	v_writelane_b32 v254, s4, 12
	s_ashr_i32 s0, s0, 1
	v_cmp_lt_u32_e64 s[8:9], v185, v162
	v_writelane_b32 v254, s5, 13
	v_lshl_add_u64 v[158:159], s[84:85], 0, v[0:1]
	v_add_u32_e32 v4, 0, v0
	v_mov_b32_e32 v0, s0
	v_writelane_b32 v254, s8, 18
	v_bfi_b32 v0, s11, v0, v3
	s_movk_i32 s1, 0x90
	v_writelane_b32 v254, s9, 19
	v_cmp_gt_u32_e64 s[8:9], v185, v162
	v_and_b32_e32 v16, 63, v3
	s_and_b32 s33, s0, 0xffffffe0
	v_mul_lo_u32 v0, v0, s1
	v_bfe_u32 v7, v3, 2, 2
	v_writelane_b32 v254, s8, 16
	v_or_b32_e32 v186, 27, v170
	v_add_u32_e32 v5, 0, v0
	v_lshlrev_b32_e32 v0, 2, v16
	v_and_b32_e32 v3, 16, v3
	v_or3_b32 v7, v7, v170, s33
	s_movk_i32 s0, 0xc0
	v_writelane_b32 v254, s9, 17
	v_cmp_lt_u32_e64 s[8:9], v186, v162
	v_and_or_b32 v3, v0, 12, v3
	v_mul_lo_u32 v7, v7, s0
	v_writelane_b32 v254, s8, 20
	v_lshlrev_b32_e32 v3, 1, v3
	v_add_u32_e32 v7, 0, v7
	v_writelane_b32 v254, s9, 21
	v_cmp_gt_u32_e64 s[8:9], v186, v162
	v_lshlrev_b32_e32 v6, 4, v17
	v_xor_b32_e32 v171, 0x80, v0
	v_lshlrev_b32_e32 v0, 3, v17
	v_cmp_gt_u32_e64 s[88:89], 32, v16
	v_mul_lo_u32 v8, v163, s1
	v_mul_lo_u32 v9, v163, s0
	v_mul_lo_u32 v10, v164, s1
	v_mul_lo_u32 v11, v164, s0
	v_mul_lo_u32 v12, v165, s1
	v_mul_lo_u32 v13, v165, s0
	v_mul_lo_u32 v14, v166, s1
	v_mul_lo_u32 v15, v166, s0
	v_mul_lo_u32 v16, v167, s1
	v_mul_lo_u32 v17, v167, s0
	v_mul_lo_u32 v18, v168, s1
	v_mul_lo_u32 v19, v168, s0
	v_or_b32_e32 v172, 1, v170
	v_or_b32_e32 v173, 2, v170
	v_or_b32_e32 v174, 3, v170
	v_or_b32_e32 v175, 8, v170
	v_or_b32_e32 v176, 9, v170
	v_or_b32_e32 v177, 10, v170
	v_or_b32_e32 v178, 11, v170
	v_or_b32_e32 v179, 16, v170
	v_or_b32_e32 v180, 17, v170
	v_or_b32_e32 v181, 18, v170
	v_or_b32_e32 v182, 19, v170
	v_or_b32_e32 v183, 24, v170
	v_or_b32_e32 v184, 25, v170
	v_writelane_b32 v254, s8, 22
	v_add_u32_e32 v20, 0xd800, v7
	v_add_u32_e32 v200, v7, v3
	s_mov_b32 s93, 0
	v_cmp_lt_u32_e64 s[2:3], v170, v162
	v_cmp_lt_u32_e64 s[76:77], v172, v162
	v_cmp_lt_u32_e64 s[16:17], v173, v162
	v_cmp_gt_u32_e64 s[18:19], v173, v162
	v_cmp_lt_u32_e64 s[20:21], v174, v162
	v_cmp_gt_u32_e64 s[22:23], v174, v162
	v_cmp_lt_u32_e64 s[24:25], v175, v162
	v_cmp_gt_u32_e64 s[26:27], v175, v162
	v_cmp_lt_u32_e64 s[28:29], v176, v162
	v_cmp_gt_u32_e64 s[30:31], v176, v162
	v_cmp_lt_u32_e64 s[34:35], v177, v162
	v_cmp_gt_u32_e64 s[36:37], v177, v162
	v_cmp_lt_u32_e64 s[38:39], v178, v162
	v_cmp_gt_u32_e64 s[40:41], v178, v162
	v_cmp_lt_u32_e64 s[42:43], v179, v162
	v_cmp_gt_u32_e64 s[44:45], v179, v162
	v_cmp_lt_u32_e64 s[46:47], v180, v162
	v_cmp_gt_u32_e64 s[48:49], v180, v162
	v_cmp_lt_u32_e64 s[4:5], v181, v162
	v_cmp_gt_u32_e64 s[52:53], v181, v162
	v_cmp_lt_u32_e64 s[54:55], v182, v162
	v_cmp_gt_u32_e64 s[56:57], v182, v162
	v_cmp_lt_u32_e64 s[58:59], v183, v162
	v_cmp_gt_u32_e64 s[60:61], v183, v162
	v_cmp_lt_u32_e64 s[62:63], v184, v162
	v_cmp_gt_u32_e64 s[64:65], v184, v162
	v_writelane_b32 v254, s9, 23
	v_or_b32_e32 v246, 0x63, v170
	v_or_b32_e32 v190, 0x6a, v170
	v_or_b32_e32 v191, 0x6b, v170
	v_or_b32_e32 v192, 0x70, v170
	v_or_b32_e32 v193, 0x71, v170
	v_or_b32_e32 v194, 0x72, v170
	v_or_b32_e32 v195, 0x73, v170
	v_or_b32_e32 v196, 0x78, v170
	v_or_b32_e32 v197, 0x79, v170
	v_or_b32_e32 v198, 0x7a, v170
	v_or_b32_e32 v199, 0x7b, v170
	v_add_u32_e32 v201, 0xfc00, v200
	v_add_u32_e32 v202, 0xfc40, v200
	v_add_u32_e32 v203, v4, v8
	v_add_u32_e32 v208, v4, v9
	v_add_u32_e32 v209, v4, v10
	v_add_u32_e32 v210, v4, v11
	v_add_u32_e32 v211, v4, v12
	v_add_u32_e32 v212, v4, v13
	v_add_u32_e32 v213, v4, v14
	v_add_u32_e32 v214, v4, v15
	v_add_u32_e32 v215, v4, v16
	v_add_u32_e32 v216, v4, v17
	v_add_u32_e32 v217, v4, v18
	v_add_u32_e32 v218, v4, v19
	v_lshlrev_b32_e32 v160, 1, v2
	v_add_u32_e32 v219, v5, v6
	v_add_u32_e32 v220, v20, v3
	v_lshlrev_b32_e32 v0, 1, v0
	v_readlane_b32 s10, v255, 41
	s_add_i32 s10, s10, 0x2e0
	s_branch .Ldb_472

; #define LAS __attribute__((address_space(3)))
; __device__ __forceinline__ void phase(LAS unsigned char* L, const u16* __restrict__ QKV, u16* OBg0, u16* OBg1, u16* OBg2, float* LSE, int first, int stride, const int tid) {
;     ...
;     for (int kr = 0; kr < nround; ++kr) {
;         const int task = DL_TASK(kr);
;         const Dec d = decode(task);
; #pragma unroll
;         for (int n = 0; n < 6; ++n) { const int id = tid + 512 * n, c = id >> 3, ch = id & 7; *(LAS v4u*)(L + O_K + c * KP + ch * 16) = pk[n]; *(LAS v4u*)(L + O_V + c * VP + ch * 16) = pv[n]; }
;         bf16x8 qf[4];
; #pragma unroll
;         for (int ks = 0; ks < 4; ++ks) qf[ks] = qn[ks];
;         __syncthreads();
;         if (kr + 1 < nround) issue(QKV, DL_TASK(kr + 1), tid, pk, pv, qn);
.Ldb_latch:
	s_add_i32 s10, s10, 0xffffffa0
	s_waitcnt vmcnt(4)
	v_mov_b64_e32 v[148:149], v[144:145]
	v_mov_b64_e32 v[152:153], v[140:141]
	v_mov_b64_e32 v[156:157], v[136:137]
	v_mov_b64_e32 v[66:67], v[130:131]
	s_cmp_lg_u32 s6, s93
	v_mov_b64_e32 v[146:147], v[142:143]
	v_mov_b64_e32 v[150:151], v[138:139]
	v_mov_b64_e32 v[154:155], v[134:135]
	v_mov_b64_e32 v[68:69], v[132:133]
	s_mov_b64 s[50:51], s[74:75]
	s_barrier
	s_cbranch_scc0 .Ldb_484

; #define LAS __attribute__((address_space(3)))
; __device__ __forceinline__ void phase(LAS unsigned char* L, const u16* __restrict__ QKV, u16* OBg0, u16* OBg1, u16* OBg2, float* LSE, int first, int stride, const int tid) {
;     ...
;     v4u pk[6], pv[6]; bf16x8 qn[4];
;     issue(QKV, DL_TASK(0), tid, pk, pv, qn);
;     for (int kr = 0; kr < nround; ++kr) {
;         const int task = DL_TASK(kr);
;         const Dec d = decode(task);
; #pragma unroll
;         for (int n = 0; n < 6; ++n) { const int id = tid + 512 * n, c = id >> 3, ch = id & 7; *(LAS v4u*)(L + O_K + c * KP + ch * 16) = pk[n]; *(LAS v4u*)(L + O_V + c * VP + ch * 16) = pv[n]; }
;         bf16x8 qf[4];
; #pragma unroll
;         for (int ks = 0; ks < 4; ++ks) qf[ks] = qn[ks];
;         __syncthreads();
;         if (kr + 1 < nround) issue(QKV, DL_TASK(kr + 1), tid, pk, pv, qn);
.Ldb_477:
	v_readlane_b32 s12, v254, 12
	s_andn2_b64 vcc, exec, s[0:1]
	v_readlane_b32 s13, v254, 13
	s_cbranch_vccnz .Ldb_479
	s_add_i32 s11, s10, 0xffffffa0
